# K-loop: pre-barrier address ops of segs 3,5,7 moved after the barrier (into ds_read issue shadow), on top of back-edge rotation
# speedup vs baseline: 1.0023x; 1.0023x over previous
.Lk_body:
	s_add_i32 s44, s4, 2
	s_add_u32 s8, s6, 0x80
	s_addc_u32 s5, s7, 0
	s_add_i32 s45, 0, 0x10000
	v_add_u32_e32 v140, s45, v234
	ds_read_b128 v[128:131], v140
	ds_read_b128 v[132:135], v140 offset:1024
	ds_read_b128 v[136:139], v140 offset:2048
	ds_read_b128 v[140:143], v140 offset:3072
	s_cmp_eq_u32 s27, s4
	s_cselect_b32 s4, s90, s8
	s_cselect_b32 s5, s91, s5
	s_cselect_b32 s9, s93, s43
	s_cselect_b32 s8, s92, s42
	v_lshl_add_u64 v[214:215], s[6:7], 0, v[206:207]
	s_add_i32 m0, s74, 0xc000
	ds_read_b128 v[144:147], v235
	ds_read_b128 v[148:151], v235 offset:1024
	ds_read_b128 v[152:155], v235 offset:2048
	ds_read_b128 v[156:159], v235 offset:3072
	ds_read_b128 v[160:163], v235 offset:4096
	ds_read_b128 v[164:167], v235 offset:5120
	ds_read_b128 v[168:171], v235 offset:6144
	ds_read_b128 v[210:213], v235 offset:7168
	global_load_lds_dwordx4 v[214:215], off
	v_lshl_add_u64 v[214:215], s[6:7], 0, v[208:209]
	s_add_i32 m0, s74, 0xe000
	s_nop 0
	global_load_lds_dwordx4 v[214:215], off
	s_waitcnt lgkmcnt(8)
	s_barrier
	s_waitcnt lgkmcnt(0)
	s_waitcnt lgkmcnt(0)
	v_mfma_f32_16x16x32_bf16 v[108:111], v[128:131], v[144:147], v[108:111]
	v_mfma_f32_16x16x32_bf16 v[104:107], v[136:139], v[144:147], v[104:107]
	v_mfma_f32_16x16x32_bf16 v[92:95], v[128:131], v[152:155], v[92:95]
	v_mfma_f32_16x16x32_bf16 v[80:83], v[136:139], v[152:155], v[80:83]
	v_mfma_f32_16x16x32_bf16 v[68:71], v[128:131], v[160:163], v[68:71]
	v_mfma_f32_16x16x32_bf16 v[56:59], v[136:139], v[160:163], v[56:59]
	v_mfma_f32_16x16x32_bf16 v[44:47], v[128:131], v[168:171], v[44:47]
	v_mfma_f32_16x16x32_bf16 v[32:35], v[136:139], v[168:171], v[32:35]
	v_mfma_f32_16x16x32_bf16 v[108:111], v[132:135], v[148:151], v[108:111]
	v_mfma_f32_16x16x32_bf16 v[104:107], v[140:143], v[148:151], v[104:107]
	v_mfma_f32_16x16x32_bf16 v[92:95], v[132:135], v[156:159], v[92:95]
	v_mfma_f32_16x16x32_bf16 v[80:83], v[140:143], v[156:159], v[80:83]
	v_mfma_f32_16x16x32_bf16 v[68:71], v[132:135], v[164:167], v[68:71]
	v_mfma_f32_16x16x32_bf16 v[56:59], v[140:143], v[164:167], v[56:59]
	v_mfma_f32_16x16x32_bf16 v[44:47], v[132:135], v[210:213], v[44:47]
	v_mfma_f32_16x16x32_bf16 v[32:35], v[140:143], v[210:213], v[32:35]
	s_barrier
	s_add_i32 s45, s45, s97
	v_add_u32_e32 v172, s3, v234
	v_lshl_add_u64 v[244:245], s[8:9], 0, v[184:185]
	s_mov_b32 m0, s45
	ds_read_b128 v[214:217], v172
	ds_read_b128 v[218:221], v172 offset:1024
	ds_read_b128 v[236:239], v172 offset:2048
	ds_read_b128 v[240:243], v172 offset:3072
	global_load_lds_dwordx4 v[244:245], off
	v_lshl_add_u64 v[246:247], s[8:9], 0, v[188:189]
	s_add_i32 m0, s45, 0x2000
	s_nop 0
	global_load_lds_dwordx4 v[246:247], off
	s_barrier
	s_waitcnt lgkmcnt(0)
	s_waitcnt lgkmcnt(0)
	v_mfma_f32_16x16x32_bf16 v[124:127], v[214:217], v[144:147], v[124:127]
	v_mfma_f32_16x16x32_bf16 v[120:123], v[236:239], v[144:147], v[120:123]
	v_mfma_f32_16x16x32_bf16 v[116:119], v[214:217], v[152:155], v[116:119]
	v_mfma_f32_16x16x32_bf16 v[112:115], v[236:239], v[152:155], v[112:115]
	v_mfma_f32_16x16x32_bf16 v[100:103], v[214:217], v[160:163], v[100:103]
	v_mfma_f32_16x16x32_bf16 v[96:99], v[236:239], v[160:163], v[96:99]
	v_mfma_f32_16x16x32_bf16 v[76:79], v[214:217], v[168:171], v[76:79]
	v_mfma_f32_16x16x32_bf16 v[72:75], v[236:239], v[168:171], v[72:75]
	v_mfma_f32_16x16x32_bf16 v[124:127], v[218:221], v[148:151], v[124:127]
	v_mfma_f32_16x16x32_bf16 v[120:123], v[240:243], v[148:151], v[120:123]
	v_mfma_f32_16x16x32_bf16 v[116:119], v[218:221], v[156:159], v[116:119]
	v_mfma_f32_16x16x32_bf16 v[112:115], v[240:243], v[156:159], v[112:115]
	v_mfma_f32_16x16x32_bf16 v[100:103], v[218:221], v[164:167], v[100:103]
	v_mfma_f32_16x16x32_bf16 v[96:99], v[240:243], v[164:167], v[96:99]
	v_mfma_f32_16x16x32_bf16 v[76:79], v[218:221], v[210:213], v[76:79]
	v_mfma_f32_16x16x32_bf16 v[72:75], v[240:243], v[210:213], v[72:75]
	s_barrier
	ds_read_b128 v[144:147], v235 offset:16384
	ds_read_b128 v[148:151], v235 offset:17408
	ds_read_b128 v[152:155], v235 offset:18432
	ds_read_b128 v[156:159], v235 offset:19456
	ds_read_b128 v[160:163], v235 offset:20480
	ds_read_b128 v[164:167], v235 offset:21504
	ds_read_b128 v[168:171], v235 offset:22528
	ds_read_b128 v[210:213], v235 offset:23552
	s_mov_b32 m0, s74
	v_lshl_add_u64 v[248:249], s[4:5], 0, v[182:183]
	global_load_lds_dwordx4 v[248:249], off
	v_lshl_add_u64 v[250:251], s[4:5], 0, v[186:187]
	s_mov_b32 m0, s56
	s_nop 0
	global_load_lds_dwordx4 v[250:251], off
	s_barrier
	s_waitcnt lgkmcnt(0)
	s_waitcnt lgkmcnt(0)
	v_mfma_f32_16x16x32_bf16 v[52:55], v[128:131], v[144:147], v[52:55]
	v_mfma_f32_16x16x32_bf16 v[48:51], v[136:139], v[144:147], v[48:51]
	v_mfma_f32_16x16x32_bf16 v[28:31], v[128:131], v[152:155], v[28:31]
	v_mfma_f32_16x16x32_bf16 v[24:27], v[136:139], v[152:155], v[24:27]
	v_mfma_f32_16x16x32_bf16 v[12:15], v[128:131], v[160:163], v[12:15]
	v_mfma_f32_16x16x32_bf16 v[8:11], v[136:139], v[160:163], v[8:11]
	v_mfma_f32_16x16x32_bf16 v[4:7], v[128:131], v[168:171], v[4:7]
	v_mfma_f32_16x16x32_bf16 v[0:3], v[136:139], v[168:171], v[0:3]
	v_mfma_f32_16x16x32_bf16 v[52:55], v[132:135], v[148:151], v[52:55]
	v_mfma_f32_16x16x32_bf16 v[48:51], v[140:143], v[148:151], v[48:51]
	v_mfma_f32_16x16x32_bf16 v[28:31], v[132:135], v[156:159], v[28:31]
	v_mfma_f32_16x16x32_bf16 v[24:27], v[140:143], v[156:159], v[24:27]
	v_mfma_f32_16x16x32_bf16 v[12:15], v[132:135], v[164:167], v[12:15]
	v_mfma_f32_16x16x32_bf16 v[8:11], v[140:143], v[164:167], v[8:11]
	v_mfma_f32_16x16x32_bf16 v[4:7], v[132:135], v[210:213], v[4:7]
	v_mfma_f32_16x16x32_bf16 v[0:3], v[140:143], v[210:213], v[0:3]
	s_barrier
	s_add_u32 s8, s8, s78
	s_addc_u32 s9, s9, 0
	s_add_i32 s45, s3, s97
	v_lshl_add_u64 v[252:253], s[8:9], 0, v[184:185]
	s_mov_b32 m0, s45
	v_lshl_add_u64 v[230:231], s[8:9], 0, v[188:189]
	global_load_lds_dwordx4 v[252:253], off
	s_add_i32 m0, s45, 0x2000
	s_nop 0
	global_load_lds_dwordx4 v[230:231], off
	s_waitcnt vmcnt(6)
	s_barrier
	v_mfma_f32_16x16x32_bf16 v[88:91], v[214:217], v[144:147], v[88:91]
	v_mfma_f32_16x16x32_bf16 v[84:87], v[236:239], v[144:147], v[84:87]
	v_mfma_f32_16x16x32_bf16 v[64:67], v[214:217], v[152:155], v[64:67]
	v_mfma_f32_16x16x32_bf16 v[60:63], v[236:239], v[152:155], v[60:63]
	v_mfma_f32_16x16x32_bf16 v[40:43], v[214:217], v[160:163], v[40:43]
	v_mfma_f32_16x16x32_bf16 v[36:39], v[236:239], v[160:163], v[36:39]
	v_mfma_f32_16x16x32_bf16 v[20:23], v[214:217], v[168:171], v[20:23]
	v_mfma_f32_16x16x32_bf16 v[16:19], v[236:239], v[168:171], v[16:19]
	v_mfma_f32_16x16x32_bf16 v[88:91], v[218:221], v[148:151], v[88:91]
	v_mfma_f32_16x16x32_bf16 v[84:87], v[240:243], v[148:151], v[84:87]
	v_mfma_f32_16x16x32_bf16 v[64:67], v[218:221], v[156:159], v[64:67]
	v_mfma_f32_16x16x32_bf16 v[60:63], v[240:243], v[156:159], v[60:63]
	v_mfma_f32_16x16x32_bf16 v[40:43], v[218:221], v[164:167], v[40:43]
	v_mfma_f32_16x16x32_bf16 v[36:39], v[240:243], v[164:167], v[36:39]
	v_mfma_f32_16x16x32_bf16 v[20:23], v[218:221], v[210:213], v[20:23]
	v_mfma_f32_16x16x32_bf16 v[16:19], v[240:243], v[210:213], v[16:19]
	s_barrier
	s_add_i32 s8, 0, 0x18000
	v_add_u32_e32 v140, s8, v234
	ds_read_b128 v[128:131], v140
	ds_read_b128 v[132:135], v140 offset:1024
	ds_read_b128 v[136:139], v140 offset:2048
	ds_read_b128 v[140:143], v140 offset:3072
	s_add_u32 s4, s4, s60
	s_addc_u32 s5, s5, 0
	s_mov_b32 m0, s57
	v_lshl_add_u64 v[214:215], s[4:5], 0, v[182:183]
	ds_read_b128 v[144:147], v235 offset:32768
	ds_read_b128 v[148:151], v235 offset:33792
	ds_read_b128 v[152:155], v235 offset:34816
	ds_read_b128 v[156:159], v235 offset:35840
	ds_read_b128 v[160:163], v235 offset:36864
	ds_read_b128 v[164:167], v235 offset:37888
	ds_read_b128 v[168:171], v235 offset:38912
	ds_read_b128 v[210:213], v235 offset:39936
	global_load_lds_dwordx4 v[214:215], off
	v_lshl_add_u64 v[214:215], s[4:5], 0, v[186:187]
	s_mov_b32 m0, s68
	s_nop 0
	global_load_lds_dwordx4 v[214:215], off
	s_waitcnt lgkmcnt(8)
	s_barrier
	s_waitcnt lgkmcnt(0)
	s_waitcnt lgkmcnt(0)
	v_mfma_f32_16x16x32_bf16 v[108:111], v[128:131], v[144:147], v[108:111]
	v_mfma_f32_16x16x32_bf16 v[104:107], v[136:139], v[144:147], v[104:107]
	v_mfma_f32_16x16x32_bf16 v[92:95], v[128:131], v[152:155], v[92:95]
	v_mfma_f32_16x16x32_bf16 v[80:83], v[136:139], v[152:155], v[80:83]
	v_mfma_f32_16x16x32_bf16 v[68:71], v[128:131], v[160:163], v[68:71]
	v_mfma_f32_16x16x32_bf16 v[56:59], v[136:139], v[160:163], v[56:59]
	v_mfma_f32_16x16x32_bf16 v[44:47], v[128:131], v[168:171], v[44:47]
	v_mfma_f32_16x16x32_bf16 v[32:35], v[136:139], v[168:171], v[32:35]
	v_mfma_f32_16x16x32_bf16 v[108:111], v[132:135], v[148:151], v[108:111]
	v_mfma_f32_16x16x32_bf16 v[104:107], v[140:143], v[148:151], v[104:107]
	v_mfma_f32_16x16x32_bf16 v[92:95], v[132:135], v[156:159], v[92:95]
	v_mfma_f32_16x16x32_bf16 v[80:83], v[140:143], v[156:159], v[80:83]
	v_mfma_f32_16x16x32_bf16 v[68:71], v[132:135], v[164:167], v[68:71]
	v_mfma_f32_16x16x32_bf16 v[56:59], v[140:143], v[164:167], v[56:59]
	v_mfma_f32_16x16x32_bf16 v[44:47], v[132:135], v[210:213], v[44:47]
	v_mfma_f32_16x16x32_bf16 v[32:35], v[140:143], v[210:213], v[32:35]
	s_barrier
	s_add_i32 s4, 0, 0x1c000
	s_add_i32 s5, s8, s97
	v_add_u32_e32 v172, s4, v234
	v_lshl_add_u64 v[244:245], v[244:245], 0, s[54:55]
	s_mov_b32 m0, s5
	ds_read_b128 v[214:217], v172
	ds_read_b128 v[218:221], v172 offset:1024
	ds_read_b128 v[236:239], v172 offset:2048
	ds_read_b128 v[240:243], v172 offset:3072
	global_load_lds_dwordx4 v[244:245], off
	v_lshl_add_u64 v[244:245], v[246:247], 0, s[54:55]
	s_add_i32 m0, s5, 0x2000
	s_nop 0
	global_load_lds_dwordx4 v[244:245], off
	s_barrier
	s_waitcnt lgkmcnt(0)
	s_waitcnt lgkmcnt(0)
	v_mfma_f32_16x16x32_bf16 v[124:127], v[214:217], v[144:147], v[124:127]
	v_mfma_f32_16x16x32_bf16 v[120:123], v[236:239], v[144:147], v[120:123]
	v_mfma_f32_16x16x32_bf16 v[116:119], v[214:217], v[152:155], v[116:119]
	v_mfma_f32_16x16x32_bf16 v[112:115], v[236:239], v[152:155], v[112:115]
	v_mfma_f32_16x16x32_bf16 v[100:103], v[214:217], v[160:163], v[100:103]
	v_mfma_f32_16x16x32_bf16 v[96:99], v[236:239], v[160:163], v[96:99]
	v_mfma_f32_16x16x32_bf16 v[76:79], v[214:217], v[168:171], v[76:79]
	v_mfma_f32_16x16x32_bf16 v[72:75], v[236:239], v[168:171], v[72:75]
	v_mfma_f32_16x16x32_bf16 v[124:127], v[218:221], v[148:151], v[124:127]
	v_mfma_f32_16x16x32_bf16 v[120:123], v[240:243], v[148:151], v[120:123]
	v_mfma_f32_16x16x32_bf16 v[116:119], v[218:221], v[156:159], v[116:119]
	v_mfma_f32_16x16x32_bf16 v[112:115], v[240:243], v[156:159], v[112:115]
	v_mfma_f32_16x16x32_bf16 v[100:103], v[218:221], v[164:167], v[100:103]
	v_mfma_f32_16x16x32_bf16 v[96:99], v[240:243], v[164:167], v[96:99]
	v_mfma_f32_16x16x32_bf16 v[76:79], v[218:221], v[210:213], v[76:79]
	v_mfma_f32_16x16x32_bf16 v[72:75], v[240:243], v[210:213], v[72:75]
	s_barrier
	ds_read_b128 v[144:147], v235 offset:49152
	ds_read_b128 v[148:151], v235 offset:50176
	ds_read_b128 v[152:155], v235 offset:51200
	ds_read_b128 v[156:159], v235 offset:52224
	ds_read_b128 v[160:163], v235 offset:53248
	ds_read_b128 v[164:167], v235 offset:54272
	ds_read_b128 v[168:171], v235 offset:55296
	ds_read_b128 v[210:213], v235 offset:56320
	s_mov_b32 m0, s69
	v_lshl_add_u64 v[244:245], v[248:249], 0, s[54:55]
	global_load_lds_dwordx4 v[244:245], off
	v_lshl_add_u64 v[244:245], v[250:251], 0, s[54:55]
	s_mov_b32 m0, s26
	s_nop 0
	global_load_lds_dwordx4 v[244:245], off
	s_barrier
	s_waitcnt lgkmcnt(0)
	s_waitcnt lgkmcnt(0)
	v_mfma_f32_16x16x32_bf16 v[52:55], v[128:131], v[144:147], v[52:55]
	v_mfma_f32_16x16x32_bf16 v[48:51], v[136:139], v[144:147], v[48:51]
	v_mfma_f32_16x16x32_bf16 v[28:31], v[128:131], v[152:155], v[28:31]
	v_mfma_f32_16x16x32_bf16 v[24:27], v[136:139], v[152:155], v[24:27]
	v_mfma_f32_16x16x32_bf16 v[12:15], v[128:131], v[160:163], v[12:15]
	v_mfma_f32_16x16x32_bf16 v[8:11], v[136:139], v[160:163], v[8:11]
	v_mfma_f32_16x16x32_bf16 v[4:7], v[128:131], v[168:171], v[4:7]
	v_mfma_f32_16x16x32_bf16 v[0:3], v[136:139], v[168:171], v[0:3]
	v_mfma_f32_16x16x32_bf16 v[52:55], v[132:135], v[148:151], v[52:55]
	v_mfma_f32_16x16x32_bf16 v[48:51], v[140:143], v[148:151], v[48:51]
	v_mfma_f32_16x16x32_bf16 v[28:31], v[132:135], v[156:159], v[28:31]
	v_mfma_f32_16x16x32_bf16 v[24:27], v[140:143], v[156:159], v[24:27]
	v_mfma_f32_16x16x32_bf16 v[12:15], v[132:135], v[164:167], v[12:15]
	v_mfma_f32_16x16x32_bf16 v[8:11], v[140:143], v[164:167], v[8:11]
	v_mfma_f32_16x16x32_bf16 v[4:7], v[132:135], v[210:213], v[4:7]
	v_mfma_f32_16x16x32_bf16 v[0:3], v[140:143], v[210:213], v[0:3]
	s_barrier
	s_add_i32 s4, s4, s97
	v_lshl_add_u64 v[128:129], v[252:253], 0, s[54:55]
	s_mov_b32 m0, s4
	s_nop 0
	global_load_lds_dwordx4 v[128:129], off
	v_lshl_add_u64 v[128:129], v[230:231], 0, s[54:55]
	s_add_i32 m0, s4, 0x2000
	s_nop 0
	global_load_lds_dwordx4 v[128:129], off
	s_waitcnt vmcnt(6)
	s_barrier
	v_mfma_f32_16x16x32_bf16 v[88:91], v[214:217], v[144:147], v[88:91]
	v_mfma_f32_16x16x32_bf16 v[84:87], v[236:239], v[144:147], v[84:87]
	v_mfma_f32_16x16x32_bf16 v[64:67], v[214:217], v[152:155], v[64:67]
	v_mfma_f32_16x16x32_bf16 v[60:63], v[236:239], v[152:155], v[60:63]
	v_mfma_f32_16x16x32_bf16 v[40:43], v[214:217], v[160:163], v[40:43]
	v_mfma_f32_16x16x32_bf16 v[36:39], v[236:239], v[160:163], v[36:39]
	v_mfma_f32_16x16x32_bf16 v[20:23], v[214:217], v[168:171], v[20:23]
	v_mfma_f32_16x16x32_bf16 v[16:19], v[236:239], v[168:171], v[16:19]
	v_mfma_f32_16x16x32_bf16 v[88:91], v[218:221], v[148:151], v[88:91]
	v_mfma_f32_16x16x32_bf16 v[84:87], v[240:243], v[148:151], v[84:87]
	v_mfma_f32_16x16x32_bf16 v[64:67], v[218:221], v[156:159], v[64:67]
	v_mfma_f32_16x16x32_bf16 v[60:63], v[240:243], v[156:159], v[60:63]
	v_mfma_f32_16x16x32_bf16 v[40:43], v[218:221], v[164:167], v[40:43]
	v_mfma_f32_16x16x32_bf16 v[36:39], v[240:243], v[164:167], v[36:39]
	v_mfma_f32_16x16x32_bf16 v[20:23], v[218:221], v[210:213], v[20:23]
	v_mfma_f32_16x16x32_bf16 v[16:19], v[240:243], v[210:213], v[16:19]
	s_add_u32 s6, s6, 0x100
	s_addc_u32 s7, s7, 0
	s_add_u32 s42, s42, 0x100
	s_addc_u32 s43, s43, 0
	s_cmp_ge_u32 s44, s73
	s_mov_b32 s4, s44
	s_cbranch_scc0 .LBB0_744
	s_barrier
	s_lshl_b32 s52, s30, 8
	s_cmp_lt_i32 s96, 2
	s_mov_b64 s[4:5], -1
	s_cbranch_scc1 .LBB0_898
	s_cmp_gt_i32 s96, 2
	s_cbranch_scc0 .LBB0_895
	s_add_i32 s30, s52, s82
	v_or_b32_e32 v210, s30, v179
	s_and_b32 s4, s10, -4
	s_cmp_lg_u32 s4, 4
	s_movk_i32 s4, 0x2000
	s_movk_i32 s6, 0x1fff
	v_or_b32_e32 v212, 16, v210
	v_cmp_gt_i32_e32 vcc, s4, v210
	v_cmp_lt_i32_e64 s[42:43], s6, v210
	s_mov_b64 s[4:5], -1
	v_ashrrev_i32_e32 v211, 31, v210
	s_movk_i32 s53, 0x1fff
	v_cmp_lt_i32_e64 s[46:47], s6, v212
	s_cbranch_scc0 .LBB0_829
	v_lshlrev_b32_e32 v128, 6, v212
	s_movk_i32 s4, 0x2000
	v_and_b32_e32 v128, 0x3f7c0, v128
	v_cmp_gt_i32_e64 s[44:45], s4, v212
	v_lshlrev_b32_e32 v219, 6, v210
	v_and_b32_e32 v144, 0x3f3c0, v219
	v_cndmask_b32_e64 v128, v225, v128, s[44:45]
	v_lshlrev_b32_e32 v172, 2, v128
	v_cndmask_b32_e32 v144, v225, v144, vcc
	v_lshl_add_u64 v[132:133], v[196:197], 0, v[172:173]
	v_lshl_add_u64 v[140:141], v[198:199], 0, v[172:173]
	v_lshlrev_b32_e32 v172, 2, v144
	v_lshl_add_u64 v[144:145], v[198:199], 0, v[172:173]
	global_load_dwordx4 v[128:131], v[132:133], off offset:16
	global_load_dwordx4 v[136:139], v[132:133], off
	s_nop 0
	global_load_dwordx4 v[132:135], v[140:141], off offset:16
	s_nop 0
	global_load_dwordx4 v[140:143], v[140:141], off
	s_nop 0
	global_load_dwordx4 v[156:159], v[144:145], off offset:16
	global_load_dwordx4 v[152:155], v[144:145], off
	v_lshl_add_u64 v[144:145], v[196:197], 0, v[172:173]
	global_load_dwordx4 v[160:163], v[144:145], off offset:16
	global_load_dwordx4 v[164:167], v[144:145], off
	s_cmp_gt_i32 s10, 3
	s_cselect_b64 s[4:5], -1, 0
	s_lshl_b32 s6, s10, 1
	s_add_i32 s7, s6, -16
	s_cmp_lt_i32 s10, 4
	s_cselect_b32 s6, s6, s7
	v_readlane_b32 s7, v255, 50
	s_or_b32 s6, s6, s7
	s_lshl_b32 s94, s6, 7
	s_ashr_i32 s95, s94, 31
	s_lshl_b64 s[6:7], s[94:95], 1
	v_lshl_add_u64 v[214:215], v[200:201], 0, s[6:7]
	s_waitcnt vmcnt(0)
	v_pk_mul_f32 v[144:145], v[126:127], v[154:155]
	v_pk_mul_f32 v[148:149], v[124:125], v[152:153]
	v_pk_fma_f32 v[146:147], v[110:111], v[166:167], v[144:145] neg_lo:[0,0,1] neg_hi:[0,0,1]
	v_pk_fma_f32 v[144:145], v[108:109], v[164:165], v[148:149] neg_lo:[0,0,1] neg_hi:[0,0,1]
	v_pk_mul_f32 v[148:149], v[122:123], v[158:159]
	v_pk_mul_f32 v[168:169], v[120:121], v[156:157]
	v_pk_fma_f32 v[150:151], v[106:107], v[162:163], v[148:149] neg_lo:[0,0,1] neg_hi:[0,0,1]
	v_pk_fma_f32 v[148:149], v[104:105], v[160:161], v[168:169] neg_lo:[0,0,1] neg_hi:[0,0,1]
	v_pk_mul_f32 v[166:167], v[126:127], v[166:167]
	v_pk_mul_f32 v[164:165], v[124:125], v[164:165]
	v_pk_mul_f32 v[162:163], v[122:123], v[162:163]
	v_pk_mul_f32 v[160:161], v[120:121], v[160:161]
	v_pk_fma_f32 v[154:155], v[110:111], v[154:155], v[166:167]
	v_pk_fma_f32 v[152:153], v[108:109], v[152:153], v[164:165]
	v_pk_fma_f32 v[158:159], v[106:107], v[158:159], v[162:163]
	v_pk_fma_f32 v[156:157], v[104:105], v[156:157], v[160:161]
	v_cvt_pk_bf16_f32 v160, v144, v145
	v_cvt_pk_bf16_f32 v161, v146, v147
	v_cvt_pk_bf16_f32 v162, v148, v149
	v_cvt_pk_bf16_f32 v163, v150, v151
	v_cvt_pk_bf16_f32 v164, v152, v153
	v_cvt_pk_bf16_f32 v165, v154, v155
	v_cvt_pk_bf16_f32 v166, v156, v157
	v_cvt_pk_bf16_f32 v167, v158, v159
	s_mov_b64 s[8:9], -1
	s_and_b64 vcc, exec, s[4:5]
	s_cbranch_vccz .LBB0_750
	s_movk_i32 s8, 0x1800
	v_mad_i64_i32 v[168:169], s[8:9], v210, s8, v[214:215]
	global_store_dwordx4 v[168:169], v[160:163], off
	global_store_dwordx4 v[168:169], v[164:167], off offset:128
	s_mov_b64 s[8:9], 0
